# k=6: second-round tiles of the three merge GEMMs spread over workgroups 0-31/32-63/64-95 with per-tile counters ordering the partial-sum hand-over; wconv on workgroups 96+
# speedup vs baseline: 1.0128x; 1.0115x over previous
; #define PG8_STAGE(bufoff, gbase, voff) do { _Pragma("unroll") for (int _i = 0; _i < 2; ++_i) \
;         __builtin_amdgcn_global_load_lds((const unsigned*)((const char*)(gbase) + (voff)[_i]), (PG8_LAS unsigned*)(lds + (bufoff) + ldsw + _i * 8192), 16, 0, 0); } while (0)
; #define PG8_WAIT_V(n) asm volatile("s_waitcnt vmcnt(" #n ")" ::: "memory")
; #define PG8_BAR __builtin_amdgcn_s_barrier()
; template <class Epi, class Sched, bool ALIGN_EPI = false, bool SP2 = false>
; __device__ __forceinline__ void gemm_phase(PG8_LAS unsigned char* lds, const Gemm g, const Sched& S, const Epi& E, const int tid_in) {
;     ...
;     const char* cA = (const char*)g.A + (size_t)cur.pm * tstep; const char* cB = (const char*)g.Bt + (size_t)cur.pn * tstep;
;     S.a_ready(cur);
;     if constexpr (SP2) {
;         PG8_STAGE(PG8_SB(0, 0), cB, voffB); PG8_STAGE(PG8_SB(0, 1), cB + hstep, voffB); PG8_STAGE(PG8_SA(0, 0), cA, voffA); PG8_STAGE(PG8_SA(0, 1), cA + hstep, voffA);
;         if (wr == 1) PG8_BAR;
;         PG8_WAIT_V(2); PG8_BAR;
;         PG8_STAGE(PG8_SB(1, 0), cB + kstep, voffB); PG8_STAGE(PG8_SA(1, 0), cA + kstep, voffA); PG8_STAGE(PG8_SB(1, 1), cB + hstep + kstep, voffB);
;         PG8_WAIT_V(6); PG8_BAR;
;     ...
;     PG8_WAIT_V(0);
;     if constexpr (!ALIGN_EPI) { if (wr == 0) PG8_BAR; }
;     PG8_BAR;
;     if constexpr (Epi::AFTER_DRAIN) { E.fused(acc, cur, wr, wc, fr, fq, lds, wid, lane); S.done(cur); }
.LBB0_183:
	s_waitcnt vmcnt(0)
	v_readlane_b32 s90, v255, 3
	v_readlane_b32 s94, v255, 5
	v_readlane_b32 s62, v255, 43
	v_readlane_b32 s76, v255, 47
	v_readlane_b32 s78, v255, 2
	v_readlane_b32 s91, v255, 4
	v_readlane_b32 s95, v255, 6
	s_movk_i32 s93, 0x2000
	s_mov_b32 s79, 0x10000
	s_mov_b32 s92, 0xbfb8aa3b
	v_readlane_b32 s63, v255, 44
	v_readlane_b32 s77, v255, 48
	v_readlane_b32 s6, v255, 49
	s_mov_b32 s67, s86
	s_barrier
	s_cmp_lg_u32 s0, 0x100
	s_cbranch_scc1 .Lmg_r0_done
	s_cmpk_lt_u32 s18, 0x101
	s_cbranch_scc1 .Lmg_r0_done
	s_sub_i32 s42, s2, 0
	s_cmpk_gt_u32 s42, 31
	s_cbranch_scc1 .Lmg_r0_done
	v_readfirstlane_b32 s98, v178
	s_cmpk_gt_u32 s98, 63
	s_cbranch_scc1 .Lmg_r0_done
	buffer_wbl2 sc1
	s_waitcnt vmcnt(0)
	v_readlane_b32 s98, v254, 57
	v_readlane_b32 s99, v254, 58
	s_lshl_b32 s42, s42, 6
	s_nop 0
	s_add_u32 s98, s98, s42
	s_addc_u32 s99, s99, 0
	v_mov_b32_e32 v2, s98
	v_mov_b32_e32 v3, s99
	v_mbcnt_lo_u32_b32 v4, -1, 0
	v_mbcnt_hi_u32_b32 v4, -1, v4
	v_mov_b32_e32 v5, 1
	v_cmp_eq_u32_e32 vcc, 0, v4
	s_and_saveexec_b64 s[98:99], vcc
	global_atomic_add v[2:3], v5, off offset:256
	s_mov_b64 exec, s[98:99]
	s_waitcnt vmcnt(0)
.Lmg_r0_done:
.LBB0_184:
	v_cndmask_b32_e64 v0, 0, 1, s[44:45]
	s_movk_i32 s42, 0x400
	v_cmp_ne_u32_e64 s[40:41], 1, v0
	s_andn2_b64 vcc, exec, s[44:45]
	v_readfirstlane_b32 s33, v178
	s_cbranch_vccnz .LBB0_205
	s_load_dwordx2 s[4:5], s[74:75], 0x110
	v_mul_lo_u32 v0, s42, v160
	v_add_lshl_u32 v130, v0, v159, 1
	v_mul_lo_u32 v0, s42, v158
	v_add_lshl_u32 v132, v0, v159, 1
	s_waitcnt lgkmcnt(0)
	s_add_u32 s3, s4, 0xa600000
	s_addc_u32 s10, s5, 0
	s_add_u32 s11, s4, 0x1a00000
	s_addc_u32 s14, s5, 0
	s_ashr_i32 s27, s2, 31
	s_lshr_b32 s4, s27, 29
	s_add_i32 s4, s2, s4
	s_ashr_i32 s36, s33, 6
	s_ashr_i32 s43, s42, 31
	s_lshr_b32 s17, s6, 9
	s_ashr_i32 s5, s4, 3
	s_and_b32 s4, s4, -8
	s_ashr_i32 s45, s33, 8
	s_lshl_b64 s[52:53], s[42:43], 8
	s_lshl_b64 s[54:55], s[42:43], 9
	s_lshl_b32 s16, s36, 10
	s_sub_i32 s4, s2, s4
	s_or_b32 s34, s17, 1
	s_cmp_lt_i32 s4, 0
	s_cselect_b32 s6, s34, s17
	s_mul_i32 s4, s4, s6
	s_add_i32 s4, s4, s5
	s_ashr_i32 s5, s4, 31
	s_lshr_b32 s5, s5, 27
	s_add_i32 s5, s4, s5
	s_ashr_i32 s6, s5, 5
	s_lshl_b32 s6, s6, 3
	s_sub_i32 s7, s1, s6
	s_min_i32 s7, s7, 8
	s_andn2_b32 s5, s5, 31
	s_sub_i32 s35, s4, s5
	s_sext_i32_i8 s4, s7
	v_cvt_f32_i32_e32 v3, s4
	v_cvt_f32_i32_e32 v2, s35
	s_xor_b32 s5, s35, s4
	s_ashr_i32 s5, s5, 30
	v_rcp_iflag_f32_e32 v4, v3
	s_or_b32 s37, s5, 1
	v_mul_lo_u32 v0, s42, v157
	v_add_lshl_u32 v0, v0, v156, 1
	v_mul_f32_e32 v4, v2, v4
	v_trunc_f32_e32 v4, v4
	v_fma_f32 v2, -v4, v3, v2
	v_cvt_i32_f32_e32 v4, v4
	v_cmp_ge_f32_e64 s[4:5], |v2|, |v3|
	s_and_b64 s[4:5], s[4:5], exec
	s_cselect_b32 s4, s37, 0
	v_readfirstlane_b32 s5, v4
	s_add_i32 s44, s5, s4
	s_mul_i32 s4, s44, s7
	s_sub_i32 s4, s35, s4
	s_sext_i32_i8 s4, s4
	s_add_i32 s78, s6, s4
	s_ashr_i32 s4, s78, 31
	s_mul_i32 s4, s54, s4
	s_mul_hi_u32 s5, s54, s78
	s_add_i32 s6, s5, s4
	s_lshr_b64 s[4:5], s[42:43], 23
	s_mul_i32 s5, s4, s78
	s_add_i32 s37, s6, s5
	s_bfe_i64 s[6:7], s[44:45], 0x80000
	s_mul_i32 s5, s54, s7
	s_mul_hi_u32 s7, s54, s6
	s_add_i32 s5, s7, s5
	s_mul_i32 s4, s4, s6
	s_add_i32 s5, s5, s4
	s_mul_i32 s4, s54, s6
	s_add_u32 s4, s11, s4
	s_addc_u32 s5, s14, s5
	s_add_i32 s35, s16, 0
	s_add_i32 m0, s35, 0x10000
	s_mul_i32 s39, s54, s78
	global_load_lds_dwordx4 v0, s[4:5]
	s_add_i32 m0, s35, 0x12000
	s_add_u32 s6, s4, s52
	global_load_lds_dwordx4 v130, s[4:5]
	s_addc_u32 s7, s5, s53
	s_add_i32 m0, s35, 0x14000
	v_mov_b32_e32 v131, v1
	global_load_lds_dwordx4 v0, s[6:7]
	s_add_i32 m0, s35, 0x16000
	v_lshl_add_u64 v[6:7], s[6:7], 0, v[0:1]
	v_lshl_add_u64 v[8:9], s[6:7], 0, v[130:131]
	global_load_lds_dwordx4 v130, s[6:7]
	s_add_u32 s6, s3, s39
	v_mul_lo_u32 v14, s42, v155
	s_addc_u32 s7, s10, s37
	s_add_i32 s37, s35, 0x2000
	v_add_lshl_u32 v134, v14, v156, 1
	s_mov_b32 m0, s35
	s_add_u32 s56, s6, s52
	global_load_lds_dwordx4 v134, s[6:7]
	s_mov_b32 m0, s37
	s_addc_u32 s57, s7, s53
	s_add_i32 s39, s35, 0x4000
	global_load_lds_dwordx4 v132, s[6:7]
	s_mov_b32 m0, s39
	s_add_i32 s62, s35, 0x6000
	global_load_lds_dwordx4 v134, s[56:57]
	s_mov_b32 m0, s62
	v_mov_b32_e32 v135, v1
	global_load_lds_dwordx4 v132, s[56:57]
	v_mov_b32_e32 v133, v1
	s_cmp_eq_u32 s45, 1
	s_mov_b32 s87, s67
	v_lshl_add_u64 v[2:3], s[4:5], 0, v[0:1]
	v_lshl_add_u64 v[4:5], s[4:5], 0, v[130:131]
	v_lshl_add_u64 v[10:11], s[6:7], 0, v[134:135]
	v_lshl_add_u64 v[12:13], s[6:7], 0, v[132:133]
	s_cselect_b64 s[56:57], -1, 0
	s_cmp_lg_u32 s45, 1
	s_cbranch_scc1 .LBB0_187
	s_barrier

;     __host__ __device__ bool next(int i, Unit& u) const {
;         const long L = (long)i * G + c; if (L >= nwg) return false;
;         int wgid = (int)L; { const int q = nwg / NXCD, r = nwg % NXCD, xcd = wgid % NXCD, off = wgid / NXCD; wgid = (xcd < r ? xcd * (q + 1) : r * (q + 1) + (xcd - r) * q) + off; }
;         const int nig = WGM * nN, gid = wgid / nig, fm = gid * WGM, gsz = (nM - fm) < WGM ? (nM - fm) : WGM;
;         u.pm = fm + ((wgid % nig) % gsz); u.pn = (wgid % nig) / gsz; return true;
.LBB0_190:
	s_add_i32 s93, s93, 1
	s_mul_i32 s33, s93, s92
	s_mul_hi_u32 s36, s93, s0
	s_add_i32 s36, s36, s33
	s_mul_i32 s33, s93, s0
	s_sub_i32 s98, s2, 32
	s_and_b32 s98, s98, 0xff
	s_cmp_eq_u32 s0, 0x100
	s_cselect_b32 s98, s98, s2
	s_add_u32 s42, s33, s98
	s_addc_u32 s43, s36, s27
	v_mov_b64_e32 v[2:3], s[18:19]
	v_cmp_ge_i64_e32 vcc, s[42:43], v[2:3]
	v_cmp_lt_i64_e64 s[44:45], s[42:43], v[2:3]
	s_cbranch_vccnz .LBB0_192
	s_ashr_i32 s33, s42, 31
	s_lshr_b32 s33, s33, 29
	s_add_i32 s33, s42, s33
	s_ashr_i32 s36, s33, 3
	s_and_b32 s33, s33, -8
	s_sub_i32 s33, s42, s33
	s_cmp_lt_i32 s33, 0
	s_cselect_b32 s42, s34, s17
	s_mul_i32 s33, s42, s33
	s_add_i32 s33, s33, s36
	s_ashr_i32 s36, s33, 31
	s_lshr_b32 s36, s36, 27
	s_add_i32 s36, s33, s36
	s_ashr_i32 s42, s36, 5
	s_lshl_b32 s42, s42, 3
	s_sub_i32 s43, s1, s42
	s_min_i32 s43, s43, 8
	s_abs_i32 s63, s43
	v_cvt_f32_u32_e32 v2, s63
	s_sub_i32 s67, 0, s63
	s_andn2_b32 s36, s36, 31
	s_sub_i32 s33, s33, s36
	v_rcp_iflag_f32_e32 v2, v2
	s_abs_i32 s36, s33
	s_xor_b32 s66, s33, s43
	s_ashr_i32 s66, s66, 31
	v_mul_f32_e32 v2, 0x4f7ffffe, v2
	v_cvt_u32_f32_e32 v2, v2
	s_nop 0
	v_readfirstlane_b32 s77, v2
	s_mul_i32 s67, s67, s77
	s_mul_hi_u32 s67, s77, s67
	s_add_i32 s77, s77, s67
	s_mul_hi_u32 s67, s36, s77
	s_mul_i32 s77, s67, s63
	s_sub_i32 s36, s36, s77
	s_add_i32 s86, s67, 1
	s_sub_i32 s77, s36, s63
	s_cmp_ge_u32 s36, s63
	s_cselect_b32 s67, s86, s67
	s_cselect_b32 s36, s77, s36
	s_add_i32 s77, s67, 1
	s_cmp_ge_u32 s36, s63
	s_cselect_b32 s36, s77, s67
	s_xor_b32 s36, s36, s66
	s_sub_i32 s94, s36, s66
	s_mul_i32 s36, s94, s43
	s_sub_i32 s33, s33, s36
	s_add_i32 s95, s33, s42

;     __device__ __forceinline__ void operator()(int row, int col, f32x4 v0, f32x4 v1) const { *(u32x4*)(G + (size_t)row * 1024 + col) = pack8(v0, v1); }
;     __device__ __forceinline__ void operator()(int row, int col, f32x4 v0, f32x4 v1) const {
;         f32x4 g0, g1; unpack8(*(const u32x4*)(GT + (size_t)row * 3072 + KB * 1024 + col), g0, g1);
;         float* mf = MF + (size_t)row * 1024 + col;
;         f32x4 r0 = g0 * v0, r1 = g1 * v1;
;         if (KB > 0) { r0 += *(const f32x4*)mf; r1 += *(const f32x4*)(mf + 4); }
; __global__ void __launch_bounds__(512, 2) mega_fwd(Args a_) {
;     ...
;                 OpMerge<1> o1{GT, MF, H}; run_gemm(ti, lds, (const bf16_t*)(ws + WS_Q), (const bf16_t*)(ws + WS_WB), Mr, 1024, 1024, o1);
.LBB0_201:
	s_cmp_lg_u32 s93, 2
	s_cbranch_scc1 .Lmg_w1_done
	s_cmp_lg_u32 s0, 0x100
	s_cbranch_scc1 .Lmg_w1_done
	v_readlane_b32 s98, v254, 57
	v_readlane_b32 s99, v254, 58
	v_readlane_b32 vcc_lo, v255, 34
	s_sub_i32 vcc_hi, s2, 32
	s_lshl_b32 vcc_hi, vcc_hi, 6
	s_add_u32 s98, s98, vcc_hi
	s_addc_u32 s99, s99, 0
	s_sub_i32 vcc_lo, vcc_lo, 7
	s_mul_i32 vcc_lo, vcc_lo, 6
	s_lshr_b32 vcc_lo, vcc_lo, 6
	s_lshl_b32 vcc_lo, vcc_lo, 1
	s_add_i32 vcc_lo, vcc_lo, 1
	v_mov_b32_e32 v166, 0
	s_mov_b32 s4, 0
.Lmg_w1_spin:
	global_load_dword v167, v166, s[98:99] offset:256 sc1
	s_waitcnt vmcnt(0)
	v_readfirstlane_b32 vcc_hi, v167
	s_cmp_eq_u32 vcc_hi, vcc_lo
	s_cbranch_scc1 .Lmg_w1_got
	s_add_i32 s4, s4, 1
	s_cmpk_gt_u32 s4, 0x4000
	s_cbranch_scc1 .Lmg_w1_got
	s_sleep 2
	s_branch .Lmg_w1_spin
.Lmg_w1_got:
	buffer_inv sc1
	s_waitcnt vmcnt(0)

; #define PG8_STAGE(bufoff, gbase, voff) do { _Pragma("unroll") for (int _i = 0; _i < 2; ++_i) \
;         __builtin_amdgcn_global_load_lds((const unsigned*)((const char*)(gbase) + (voff)[_i]), (PG8_LAS unsigned*)(lds + (bufoff) + ldsw + _i * 8192), 16, 0, 0); } while (0)
; #define PG8_WAIT_V(n) asm volatile("s_waitcnt vmcnt(" #n ")" ::: "memory")
; #define PG8_BAR __builtin_amdgcn_s_barrier()
; template <class Epi, class Sched, bool ALIGN_EPI = false, bool SP2 = false>
; __device__ __forceinline__ void gemm_phase(PG8_LAS unsigned char* lds, const Gemm g, const Sched& S, const Epi& E, const int tid_in) {
;     ...
;     const char* cA = (const char*)g.A + (size_t)cur.pm * tstep; const char* cB = (const char*)g.Bt + (size_t)cur.pn * tstep;
;     S.a_ready(cur);
;     if constexpr (SP2) {
;         PG8_STAGE(PG8_SB(0, 0), cB, voffB); PG8_STAGE(PG8_SB(0, 1), cB + hstep, voffB); PG8_STAGE(PG8_SA(0, 0), cA, voffA); PG8_STAGE(PG8_SA(0, 1), cA + hstep, voffA);
;         if (wr == 1) PG8_BAR;
;         PG8_WAIT_V(2); PG8_BAR;
;         PG8_STAGE(PG8_SB(1, 0), cB + kstep, voffB); PG8_STAGE(PG8_SA(1, 0), cA + kstep, voffA); PG8_STAGE(PG8_SB(1, 1), cB + hstep + kstep, voffB);
;         PG8_WAIT_V(6); PG8_BAR;
;     ...
;     PG8_WAIT_V(0);
;     if constexpr (!ALIGN_EPI) { if (wr == 0) PG8_BAR; }
;     PG8_BAR;
;     if constexpr (Epi::AFTER_DRAIN) { E.fused(acc, cur, wr, wc, fr, fq, lds, wid, lane); S.done(cur); }
.LBB0_204:
	s_waitcnt vmcnt(0)
	v_readlane_b32 s90, v255, 3
	v_readlane_b32 s94, v255, 5
	v_readlane_b32 s62, v255, 43
	v_readlane_b32 s76, v255, 47
	v_readlane_b32 s78, v255, 2
	v_readlane_b32 s91, v255, 4
	v_readlane_b32 s95, v255, 6
	s_movk_i32 s93, 0x2000
	s_mov_b32 s79, 0x10000
	s_mov_b32 s92, 0xbfb8aa3b
	v_readlane_b32 s63, v255, 44
	v_readlane_b32 s77, v255, 48
	v_readlane_b32 s6, v255, 49
	s_mov_b32 s67, s87
	s_barrier
	s_cmp_lg_u32 s0, 0x100
	s_cbranch_scc1 .Lmg_r1_done
	s_cmpk_lt_u32 s18, 0x101
	s_cbranch_scc1 .Lmg_r1_done
	s_sub_i32 s42, s2, 32
	s_cmpk_gt_u32 s42, 31
	s_cbranch_scc1 .Lmg_r1_done
	v_readfirstlane_b32 s98, v178
	s_cmpk_gt_u32 s98, 63
	s_cbranch_scc1 .Lmg_r1_done
	buffer_wbl2 sc1
	s_waitcnt vmcnt(0)
	v_readlane_b32 s98, v254, 57
	v_readlane_b32 s99, v254, 58
	s_lshl_b32 s42, s42, 6
	s_nop 0
	s_add_u32 s98, s98, s42
	s_addc_u32 s99, s99, 0
	v_mov_b32_e32 v2, s98
	v_mov_b32_e32 v3, s99
	v_mbcnt_lo_u32_b32 v4, -1, 0
	v_mbcnt_hi_u32_b32 v4, -1, v4
	v_mov_b32_e32 v5, 1
	v_cmp_eq_u32_e32 vcc, 0, v4
	s_and_saveexec_b64 s[98:99], vcc
	global_atomic_add v[2:3], v5, off offset:256
	s_mov_b64 exec, s[98:99]
	s_waitcnt vmcnt(0)
.Lmg_r1_done:
.LBB0_205:
	s_movk_i32 s42, 0x400
	s_and_b64 vcc, exec, s[40:41]
	v_readfirstlane_b32 s27, v178
	s_cbranch_vccnz .LBB0_227
	s_load_dwordx2 s[4:5], s[74:75], 0x110
	v_mul_lo_u32 v0, s42, v160
	v_add_lshl_u32 v130, v0, v159, 1
	v_mul_lo_u32 v0, s42, v158
	v_add_lshl_u32 v132, v0, v159, 1
	s_waitcnt lgkmcnt(0)
	s_add_u32 s3, s4, 0x29e00000
	s_addc_u32 s10, s5, 0
	s_add_u32 s11, s4, 0x1c00000
	s_addc_u32 s14, s5, 0
	s_ashr_i32 s34, s2, 31
	s_lshr_b32 s4, s34, 29
	s_add_i32 s4, s2, s4
	s_ashr_i32 s33, s27, 6
	s_ashr_i32 s43, s42, 31
	s_lshr_b32 s17, s6, 9
	s_ashr_i32 s5, s4, 3
	s_and_b32 s4, s4, -8
	s_ashr_i32 s36, s27, 8
	s_lshl_b64 s[44:45], s[42:43], 8
	s_lshl_b64 s[52:53], s[42:43], 9
	s_lshl_b32 s16, s33, 10
	s_sub_i32 s4, s2, s4
	s_or_b32 s35, s17, 1
	s_cmp_lt_i32 s4, 0
	s_cselect_b32 s6, s35, s17
	s_mul_i32 s4, s4, s6
	s_add_i32 s4, s4, s5
	s_ashr_i32 s5, s4, 31
	s_lshr_b32 s5, s5, 27
	s_add_i32 s5, s4, s5
	s_ashr_i32 s6, s5, 5
	s_lshl_b32 s6, s6, 3
	s_sub_i32 s7, s1, s6
	s_min_i32 s7, s7, 8
	s_andn2_b32 s5, s5, 31
	s_sub_i32 s37, s4, s5
	s_sext_i32_i8 s4, s7
	v_cvt_f32_i32_e32 v3, s4
	v_cvt_f32_i32_e32 v2, s37
	s_xor_b32 s5, s37, s4
	s_ashr_i32 s5, s5, 30
	v_rcp_iflag_f32_e32 v4, v3
	s_or_b32 s39, s5, 1
	v_mul_lo_u32 v0, s42, v157
	v_add_lshl_u32 v0, v0, v156, 1
	v_mul_f32_e32 v4, v2, v4
	v_trunc_f32_e32 v4, v4
	v_fma_f32 v2, -v4, v3, v2
	v_cvt_i32_f32_e32 v4, v4
	v_cmp_ge_f32_e64 s[4:5], |v2|, |v3|
	s_and_b64 s[4:5], s[4:5], exec
	s_cselect_b32 s4, s39, 0
	v_readfirstlane_b32 s5, v4
	s_add_i32 s40, s5, s4
	s_mul_i32 s4, s40, s7
	s_sub_i32 s4, s37, s4
	s_sext_i32_i8 s4, s4
	s_add_i32 s78, s6, s4
	s_ashr_i32 s4, s78, 31
	s_mul_i32 s4, s52, s4
	s_mul_hi_u32 s5, s52, s78
	s_add_i32 s6, s5, s4
	s_lshr_b64 s[4:5], s[42:43], 23
	s_mul_i32 s5, s4, s78
	s_mul_i32 s41, s52, s78
	s_add_i32 s39, s6, s5
	s_bfe_i64 s[6:7], s[40:41], 0x80000
	s_mul_i32 s5, s52, s7
	s_mul_hi_u32 s7, s52, s6
	s_add_i32 s5, s7, s5
	s_mul_i32 s4, s4, s6
	s_add_i32 s5, s5, s4
	s_mul_i32 s4, s52, s6
	s_add_u32 s4, s11, s4
	s_addc_u32 s5, s14, s5
	s_add_i32 s37, s16, 0
	s_add_i32 m0, s37, 0x10000
	v_mov_b32_e32 v131, v1
	global_load_lds_dwordx4 v0, s[4:5]
	s_add_i32 m0, s37, 0x12000
	s_add_u32 s6, s4, s44
	global_load_lds_dwordx4 v130, s[4:5]
	s_addc_u32 s7, s5, s45
	s_add_i32 m0, s37, 0x14000
	v_lshl_add_u64 v[6:7], s[6:7], 0, v[0:1]
	global_load_lds_dwordx4 v0, s[6:7]
	s_add_i32 m0, s37, 0x16000
	v_lshl_add_u64 v[8:9], s[6:7], 0, v[130:131]
	global_load_lds_dwordx4 v130, s[6:7]
	s_add_u32 s6, s3, s41
	v_mul_lo_u32 v14, s42, v155
	s_addc_u32 s7, s10, s39
	s_add_i32 s39, s37, 0x2000
	v_add_lshl_u32 v134, v14, v156, 1
	s_mov_b32 m0, s37
	s_add_u32 s54, s6, s44
	global_load_lds_dwordx4 v134, s[6:7]
	s_mov_b32 m0, s39
	s_addc_u32 s55, s7, s45
	s_add_i32 s62, s37, 0x4000
	global_load_lds_dwordx4 v132, s[6:7]
	s_mov_b32 m0, s62
	s_add_i32 s72, s37, 0x6000
	global_load_lds_dwordx4 v134, s[54:55]
	s_mov_b32 m0, s72
	v_mov_b32_e32 v135, v1
	global_load_lds_dwordx4 v132, s[54:55]
	v_mov_b32_e32 v133, v1
	s_cmp_eq_u32 s36, 1
	s_mov_b32 s86, s67
	v_lshl_add_u64 v[2:3], s[4:5], 0, v[0:1]
	v_lshl_add_u64 v[4:5], s[4:5], 0, v[130:131]
	v_lshl_add_u64 v[10:11], s[6:7], 0, v[134:135]
	v_lshl_add_u64 v[12:13], s[6:7], 0, v[132:133]
	s_cselect_b64 s[54:55], -1, 0
	s_cmp_lg_u32 s36, 1
	s_cbranch_scc1 .LBB0_208
	s_barrier

;     __host__ __device__ bool next(int i, Unit& u) const {
;         const long L = (long)i * G + c; if (L >= nwg) return false;
;         int wgid = (int)L; { const int q = nwg / NXCD, r = nwg % NXCD, xcd = wgid % NXCD, off = wgid / NXCD; wgid = (xcd < r ? xcd * (q + 1) : r * (q + 1) + (xcd - r) * q) + off; }
;         const int nig = WGM * nN, gid = wgid / nig, fm = gid * WGM, gsz = (nM - fm) < WGM ? (nM - fm) : WGM;
;         u.pm = fm + ((wgid % nig) % gsz); u.pn = (wgid % nig) / gsz; return true;
.LBB0_211:
	s_add_i32 s94, s94, 1
	s_mul_i32 s33, s94, s93
	s_mul_hi_u32 s36, s94, s0
	s_add_i32 s36, s36, s33
	s_mul_i32 s33, s94, s0
	s_sub_i32 s98, s2, 64
	s_and_b32 s98, s98, 0xff
	s_cmp_eq_u32 s0, 0x100
	s_cselect_b32 s98, s98, s2
	s_add_u32 s40, s33, s98
	s_addc_u32 s41, s36, s34
	v_mov_b64_e32 v[2:3], s[18:19]
	v_cmp_ge_i64_e32 vcc, s[40:41], v[2:3]
	v_cmp_lt_i64_e64 s[42:43], s[40:41], v[2:3]
	s_cbranch_vccnz .LBB0_213
	s_ashr_i32 s27, s40, 31
	s_lshr_b32 s27, s27, 29
	s_add_i32 s27, s40, s27
	s_ashr_i32 s33, s27, 3
	s_and_b32 s27, s27, -8
	s_sub_i32 s27, s40, s27
	s_cmp_lt_i32 s27, 0
	s_cselect_b32 s36, s35, s17
	s_mul_i32 s27, s36, s27
	s_add_i32 s27, s27, s33
	s_ashr_i32 s33, s27, 31
	s_lshr_b32 s33, s33, 27
	s_add_i32 s33, s27, s33
	s_ashr_i32 s36, s33, 5
	s_lshl_b32 s36, s36, 3
	s_sub_i32 s40, s1, s36
	s_min_i32 s40, s40, 8
	s_abs_i32 s41, s40
	v_cvt_f32_u32_e32 v2, s41
	s_sub_i32 s61, 0, s41
	s_andn2_b32 s33, s33, 31
	s_sub_i32 s27, s27, s33
	v_rcp_iflag_f32_e32 v2, v2
	s_abs_i32 s33, s27
	s_xor_b32 s60, s27, s40
	s_ashr_i32 s60, s60, 31
	v_mul_f32_e32 v2, 0x4f7ffffe, v2
	v_cvt_u32_f32_e32 v2, v2
	s_nop 0
	v_readfirstlane_b32 s63, v2
	s_mul_i32 s61, s61, s63
	s_mul_hi_u32 s61, s63, s61
	s_add_i32 s63, s63, s61
	s_mul_hi_u32 s61, s33, s63
	s_mul_i32 s63, s61, s41
	s_sub_i32 s33, s33, s63
	s_add_i32 s66, s61, 1
	s_sub_i32 s63, s33, s41
	s_cmp_ge_u32 s33, s41
	s_cselect_b32 s61, s66, s61
	s_cselect_b32 s33, s63, s33
	s_add_i32 s63, s61, 1
	s_cmp_ge_u32 s33, s41
	s_cselect_b32 s33, s63, s61
	s_xor_b32 s33, s33, s60
	s_sub_i32 s95, s33, s60
	s_mul_i32 s33, s95, s40
	s_sub_i32 s27, s27, s33
	s_add_i32 s27, s27, s36

;     __device__ __forceinline__ void operator()(int row, int col, f32x4 v0, f32x4 v1) const { *(u32x4*)(G + (size_t)row * 1024 + col) = pack8(v0, v1); }
;     __device__ __forceinline__ void operator()(int row, int col, f32x4 v0, f32x4 v1) const {
;         f32x4 g0, g1; unpack8(*(const u32x4*)(GT + (size_t)row * 3072 + KB * 1024 + col), g0, g1);
;         float* mf = MF + (size_t)row * 1024 + col;
;         f32x4 r0 = g0 * v0, r1 = g1 * v1;
;         if (KB > 0) { r0 += *(const f32x4*)mf; r1 += *(const f32x4*)(mf + 4); }
; __global__ void __launch_bounds__(512, 2) mega_fwd(Args a_) {
;     ...
;                 OpMerge<2> o2{GT, MF, H}; run_gemm(ti, lds, (const bf16_t*)(ws + WS_Y1), (const bf16_t*)(ws + WS_WC), Mr, 1024, 1024, o2);
.LBB0_223:
	s_cmp_lg_u32 s94, 2
	s_cbranch_scc1 .Lmg_w2_done
	s_cmp_lg_u32 s0, 0x100
	s_cbranch_scc1 .Lmg_w2_done
	v_readlane_b32 s98, v254, 57
	v_readlane_b32 s99, v254, 58
	v_readlane_b32 vcc_lo, v255, 34
	s_sub_i32 vcc_hi, s2, 64
	s_lshl_b32 vcc_hi, vcc_hi, 6
	s_add_u32 s98, s98, vcc_hi
	s_addc_u32 s99, s99, 0
	s_sub_i32 vcc_lo, vcc_lo, 7
	s_mul_i32 vcc_lo, vcc_lo, 6
	s_lshr_b32 vcc_lo, vcc_lo, 6
	s_lshl_b32 vcc_lo, vcc_lo, 1
	s_add_i32 vcc_lo, vcc_lo, 2
	v_mov_b32_e32 v140, 0
	s_mov_b32 s4, 0
.Lmg_w2_spin:
	global_load_dword v141, v140, s[98:99] offset:256 sc1
	s_waitcnt vmcnt(0)
	v_readfirstlane_b32 vcc_hi, v141
	s_cmp_eq_u32 vcc_hi, vcc_lo
	s_cbranch_scc1 .Lmg_w2_got
	s_add_i32 s4, s4, 1
	s_cmpk_gt_u32 s4, 0x4000
	s_cbranch_scc1 .Lmg_w2_got
	s_sleep 2
	s_branch .Lmg_w2_spin

; __global__ void __launch_bounds__(512, 2) mega_fwd(Args a_) {
;     ...
;                 if (ctx_out && ti.nblk > 64 && ti.bid >= 32) ph_wconv(a, l + 1, lds, (ti.bid - 32) * 8 + wv, (ti.nblk - 32) * 8, lane, wv, 1);
;                 else if (ctx_out && ti.nblk <= 64) ph_wconv(a, l + 1, lds, gw, ngw, lane, wv, 1);
.LBB0_227:
	s_cmp_gt_i32 s0, 64
	s_cselect_b64 s[4:5], -1, 0
	s_and_b64 s[4:5], s[76:77], s[4:5]
	s_cmp_eq_u32 s0, 0x100
	s_cselect_b32 s6, 95, 31
	s_cmp_gt_i32 s2, s6
	s_cselect_b64 s[6:7], -1, 0
	s_and_b64 s[4:5], s[4:5], s[6:7]
	v_readlane_b32 s6, v255, 50
	s_andn2_b64 vcc, exec, s[4:5]
	s_mov_b64 s[4:5], -1
	s_mov_b32 s14, s6
	v_readlane_b32 s7, v255, 51
	s_cbranch_vccz .LBB0_257
	s_cmpk_lt_i32 s0, 0x41
	s_cselect_b64 s[4:5], -1, 0
	s_and_b64 s[4:5], s[76:77], s[4:5]
	s_andn2_b64 vcc, exec, s[4:5]
	s_cbranch_vccnz .LBB0_256
	s_add_i32 s44, s62, 1
	s_cmpk_lt_i32 s14, 0x16d0
	s_mov_b64 s[4:5], -1
	s_cbranch_scc1 .LBB0_231
	s_ashr_i32 s45, s44, 31
	s_mov_b64 s[4:5], 0

; __device__ __forceinline__ void ph_wconv(CArgs& a, int l, unsigned char* ldsg, int gw, int ngw, int lane, int wv, int mask) {
;     ...
;     if (mask & 1) for (int it = gw; it < I_IN; it += ngw) transpose_item<1>(a.in[8] + (size_t)l * 1024 * 11680, 1024, 11680, (bf16_t*)(ws + WS_WIN), scr, it, lane);
; __global__ void __launch_bounds__(512, 2) mega_fwd(Args a_) {
;     ...
;                 if (ctx_out && ti.nblk > 64 && ti.bid >= 32) ph_wconv(a, l + 1, lds, (ti.bid - 32) * 8 + wv, (ti.nblk - 32) * 8, lane, wv, 1);
;                 else if (ctx_out && ti.nblk <= 64) ph_wconv(a, l + 1, lds, gw, ngw, lane, wv, 1);
.LBB0_257:
	s_andn2_b64 vcc, exec, s[4:5]
	s_cbranch_vccnz .LBB0_285
	s_movk_i32 s99, 0xff00
	s_cmp_eq_u32 s0, 0x100
	s_cselect_b32 s99, 0xfffffd00, s99
	s_add_i32 s44, s62, 1
	s_add_i32 s3, s14, s99
	s_cmpk_lt_i32 s3, 0x16d0
	s_mov_b64 s[4:5], -1
	s_cbranch_scc1 .LBB0_260
	s_ashr_i32 s45, s44, 31
	s_mov_b64 s[4:5], 0
.LBB0_260:
	s_andn2_b64 vcc, exec, s[4:5]
	s_add_i32 s1, s80, s99
	s_cbranch_vccnz .LBB0_265
	v_readlane_b32 s4, v255, 42
	s_mul_i32 s6, s4, 0x2200
	s_load_dwordx2 s[4:5], s[74:75], 0x40
	s_add_i32 s6, s6, 0
	s_ashr_i32 s45, s44, 31
	s_mul_i32 s10, s44, 0x2da0000
	s_mul_hi_i32 s7, s44, 0x2da0000
	s_waitcnt lgkmcnt(0)
	s_add_u32 s4, s4, s10
	s_addc_u32 s5, s5, s7
	v_and_b32_e32 v0, 0x7c, v148
	v_lshl_add_u64 v[4:5], s[4:5], 0, v[0:1]
	s_load_dwordx2 s[4:5], s[74:75], 0x110
	v_add_u32_e32 v6, s6, v0
	v_lshlrev_b32_e32 v0, 3, v180
	v_and_b32_e32 v0, 56, v0
	v_lshrrev_b32_e32 v12, 3, v180
	v_mul_u32_u24_e32 v3, 0x84, v0
	v_lshlrev_b32_e32 v0, 1, v0
	v_lshrrev_b32_e32 v2, 5, v180
	s_waitcnt lgkmcnt(0)
	v_lshl_add_u64 v[8:9], s[4:5], 0, v[0:1]
	s_mov_b64 s[4:5], 0x100000
	v_lshlrev_b32_e32 v0, 2, v12
	v_lshl_add_u64 v[8:9], v[8:9], 0, s[4:5]
	v_add3_u32 v13, s6, v3, v0
	v_or_b32_e32 v14, 8, v12
	v_or_b32_e32 v15, 16, v12
	v_or_b32_e32 v16, 24, v12
	v_mov_b32_e32 v3, v2
	s_mov_b32 s4, s3
